# nt hint also on the GEMM4 epilogue y stores
# baseline (speedup 1.0000x reference)
;     __device__ __forceinline__ void operator()(const f32x4 (&acc)[2][2][4][2], const Unit& u, int wr, int wc, int fr, int fq) const {
;     ...
;         for (int ai = 0; ai < 2; ++ai) { u32x2 hw[4][2][2];
; #pragma unroll
;             for (int m = 0; m < 4; ++m)
; #pragma unroll
;                 for (int bj = 0; bj < 2; ++bj)
; #pragma unroll
;                     for (int n = 0; n < 2; ++n) hw[m][bj][n] = *(const u32x2*)(H1B + (size_t)(row0 + ai * HALF + m * 16) * 4096 + col0 + bj * HALF + n * 16);
; #pragma unroll
;             for (int m = 0; m < 4; ++m) { const int row = row0 + ai * HALF + m * 16;
;                 float* dst = (row >= 272 && row < G_MV) ? yp + (size_t)(row - 272) * 4096 : nullptr;
;                 if (dst) {
; #pragma unroll
;                     for (int bj = 0; bj < 2; ++bj)
; #pragma unroll
;                         for (int n = 0; n < 2; ++n) { const int c = col0 + bj * HALF + n * 16; const u32x2 w = hw[m][bj][n]; f32x4 h;
;                             h[0] = __builtin_bit_cast(float, w.x << 16); h[1] = __builtin_bit_cast(float, w.x & 0xffff0000u); h[2] = __builtin_bit_cast(float, w.y << 16); h[3] = __builtin_bit_cast(float, w.y & 0xffff0000u);
;                             *(f32x4*)(dst + c) = h + acc[ai][bj][m][n]; } } } }
.LBB0_3526:
	v_lshl_add_u32 v146, s4, 8, v136
	v_or_b32_e32 v150, 16, v146
	v_ashrrev_i32_e32 v145, 31, v144
	v_ashrrev_i32_e32 v151, 31, v150
	v_lshl_add_u64 v[148:149], v[144:145], 1, s[10:11]
	v_lshlrev_b64 v[150:151], 13, v[150:151]
	v_lshl_add_u64 v[150:151], v[148:149], 0, v[150:151]
	global_load_dwordx2 v[174:175], v[150:151], off
	global_load_dwordx2 v[172:173], v[150:151], off offset:32
	global_load_dwordx2 v[170:171], v[150:151], off offset:256
	global_load_dwordx2 v[168:169], v[150:151], off offset:288
	v_or_b32_e32 v150, 32, v146
	v_ashrrev_i32_e32 v151, 31, v150
	v_lshlrev_b64 v[150:151], 13, v[150:151]
	v_lshl_add_u64 v[150:151], v[148:149], 0, v[150:151]
	global_load_dwordx2 v[166:167], v[150:151], off
	global_load_dwordx2 v[164:165], v[150:151], off offset:32
	global_load_dwordx2 v[162:163], v[150:151], off offset:256
	global_load_dwordx2 v[160:161], v[150:151], off offset:288
	v_or_b32_e32 v150, 48, v146
	v_ashrrev_i32_e32 v151, 31, v150
	v_lshlrev_b64 v[150:151], 13, v[150:151]
	v_lshl_add_u64 v[150:151], v[148:149], 0, v[150:151]
	global_load_dwordx2 v[158:159], v[150:151], off
	global_load_dwordx2 v[156:157], v[150:151], off offset:32
	global_load_dwordx2 v[154:155], v[150:151], off offset:256
	global_load_dwordx2 v[152:153], v[150:151], off offset:288
	v_add_u32_e32 v134, 0xfffffef0, v146
	v_cmp_gt_u32_e32 vcc, s55, v134
	s_and_b64 s[4:5], vcc, s[22:23]
	v_lshlrev_b32_e32 v150, 13, v146
	s_and_saveexec_b64 s[38:39], s[4:5]
	s_cbranch_execz .LBB0_3528
	v_mov_b32_e32 v151, v135
	v_lshl_add_u64 v[180:181], v[148:149], 0, v[150:151]
	global_load_dwordx2 v[182:183], v[180:181], off
	global_load_dwordx2 v[184:185], v[180:181], off offset:32
	global_load_dwordx2 v[186:187], v[180:181], off offset:256
	s_nop 0
	global_load_dwordx2 v[180:181], v[180:181], off offset:288
	v_lshlrev_b32_e32 v134, 14, v134
	v_lshl_add_u64 v[188:189], s[8:9], 0, v[134:135]
	v_lshl_add_u64 v[188:189], v[144:145], 2, v[188:189]
	s_waitcnt vmcnt(0)
	v_lshlrev_b32_e32 v190, 16, v182
	v_and_b32_e32 v191, 0xffff0000, v182
	v_lshlrev_b32_e32 v182, 16, v183
	v_and_b32_e32 v183, 0xffff0000, v183
	v_lshlrev_b32_e32 v192, 16, v184
	v_and_b32_e32 v193, 0xffff0000, v184
	v_lshlrev_b32_e32 v184, 16, v185
	v_and_b32_e32 v185, 0xffff0000, v185
	v_lshlrev_b32_e32 v194, 16, v186
	v_and_b32_e32 v195, 0xffff0000, v186
	v_lshlrev_b32_e32 v186, 16, v187
	v_and_b32_e32 v187, 0xffff0000, v187
	v_lshlrev_b32_e32 v196, 16, v180
	v_and_b32_e32 v197, 0xffff0000, v180
	v_lshlrev_b32_e32 v180, 16, v181
	v_and_b32_e32 v181, 0xffff0000, v181
	v_pk_add_f32 v[128:129], v[128:129], v[182:183]
	v_pk_add_f32 v[126:127], v[126:127], v[190:191]
	v_pk_add_f32 v[124:125], v[124:125], v[184:185]
	v_pk_add_f32 v[122:123], v[122:123], v[192:193]
	v_pk_add_f32 v[120:121], v[120:121], v[186:187]
	v_pk_add_f32 v[118:119], v[118:119], v[194:195]
	v_pk_add_f32 v[116:117], v[116:117], v[180:181]
	v_pk_add_f32 v[114:115], v[114:115], v[196:197]
	global_store_dwordx4 v[188:189], v[126:129], off nt
	global_store_dwordx4 v[188:189], v[122:125], off offset:64 nt
	global_store_dwordx4 v[188:189], v[118:121], off offset:512 nt
	global_store_dwordx4 v[188:189], v[114:117], off offset:576 nt
.LBB0_3528:
	s_or_b64 exec, exec, s[38:39]
	s_nop 0
	v_add_u32_e32 v114, 0xffffff00, v146
	v_cmp_gt_u32_e32 vcc, s55, v114
	s_and_b64 s[4:5], vcc, s[22:23]
	s_and_saveexec_b64 s[38:39], s[4:5]
	s_cbranch_execz .LBB0_3530
	v_lshlrev_b32_e32 v134, 14, v114
	v_lshl_add_u64 v[114:115], s[8:9], 0, v[134:135]
	s_waitcnt vmcnt(0)
	v_lshlrev_b32_e32 v116, 16, v174
	v_and_b32_e32 v117, 0xffff0000, v174
	v_lshlrev_b32_e32 v118, 16, v175
	v_and_b32_e32 v119, 0xffff0000, v175
	v_pk_add_f32 v[112:113], v[112:113], v[118:119]
	v_pk_add_f32 v[110:111], v[110:111], v[116:117]
	v_lshl_add_u64 v[114:115], v[144:145], 2, v[114:115]
	global_store_dwordx4 v[114:115], v[110:113], off nt
	s_nop 1
	v_lshlrev_b32_e32 v110, 16, v172
	v_and_b32_e32 v111, 0xffff0000, v172
	v_lshlrev_b32_e32 v112, 16, v173
	v_and_b32_e32 v113, 0xffff0000, v173
	v_pk_add_f32 v[108:109], v[108:109], v[112:113]
	v_pk_add_f32 v[106:107], v[106:107], v[110:111]
	global_store_dwordx4 v[114:115], v[106:109], off offset:64 nt
	s_nop 1
	v_lshlrev_b32_e32 v106, 16, v170
	v_and_b32_e32 v107, 0xffff0000, v170
	v_lshlrev_b32_e32 v108, 16, v171
	v_and_b32_e32 v109, 0xffff0000, v171
	v_pk_add_f32 v[104:105], v[104:105], v[108:109]
	v_pk_add_f32 v[102:103], v[102:103], v[106:107]
	global_store_dwordx4 v[114:115], v[102:105], off offset:512 nt
	s_nop 1
	v_lshlrev_b32_e32 v102, 16, v168
	v_and_b32_e32 v103, 0xffff0000, v168
	v_lshlrev_b32_e32 v104, 16, v169
	v_and_b32_e32 v105, 0xffff0000, v169
	v_pk_add_f32 v[100:101], v[100:101], v[104:105]
	v_pk_add_f32 v[98:99], v[98:99], v[102:103]
	global_store_dwordx4 v[114:115], v[98:101], off offset:576 nt
.LBB0_3530:
	s_or_b64 exec, exec, s[38:39]
	s_nop 0
	v_add_u32_e32 v98, 0xffffff10, v146
	v_cmp_gt_u32_e32 vcc, s55, v98
	s_and_b64 s[4:5], vcc, s[22:23]
	s_and_saveexec_b64 s[38:39], s[4:5]
	s_cbranch_execz .LBB0_3532
	v_lshlrev_b32_e32 v134, 14, v98
	v_lshl_add_u64 v[98:99], s[8:9], 0, v[134:135]
	s_waitcnt vmcnt(0)
	v_lshlrev_b32_e32 v100, 16, v166
	v_and_b32_e32 v101, 0xffff0000, v166
	v_lshlrev_b32_e32 v102, 16, v167
	v_and_b32_e32 v103, 0xffff0000, v167
	v_pk_add_f32 v[96:97], v[96:97], v[102:103]
	v_pk_add_f32 v[94:95], v[94:95], v[100:101]
	v_lshl_add_u64 v[98:99], v[144:145], 2, v[98:99]
	global_store_dwordx4 v[98:99], v[94:97], off nt
	s_nop 1
	v_lshlrev_b32_e32 v94, 16, v164
	v_and_b32_e32 v95, 0xffff0000, v164
	v_lshlrev_b32_e32 v96, 16, v165
	v_and_b32_e32 v97, 0xffff0000, v165
	v_pk_add_f32 v[92:93], v[92:93], v[96:97]
	v_pk_add_f32 v[90:91], v[90:91], v[94:95]
	global_store_dwordx4 v[98:99], v[90:93], off offset:64 nt
	s_nop 1
	v_lshlrev_b32_e32 v90, 16, v162
	v_and_b32_e32 v91, 0xffff0000, v162
	v_lshlrev_b32_e32 v92, 16, v163
	v_and_b32_e32 v93, 0xffff0000, v163
	v_pk_add_f32 v[88:89], v[88:89], v[92:93]
	v_pk_add_f32 v[86:87], v[86:87], v[90:91]
	global_store_dwordx4 v[98:99], v[86:89], off offset:512 nt
	s_nop 1
	v_lshlrev_b32_e32 v86, 16, v160
	v_and_b32_e32 v87, 0xffff0000, v160
	v_lshlrev_b32_e32 v88, 16, v161
	v_and_b32_e32 v89, 0xffff0000, v161
	v_pk_add_f32 v[84:85], v[84:85], v[88:89]
	v_pk_add_f32 v[82:83], v[82:83], v[86:87]
	global_store_dwordx4 v[98:99], v[82:85], off offset:576 nt
;     __device__ __forceinline__ void operator()(const f32x4 (&acc)[2][2][4][2], const Unit& u, int wr, int wc, int fr, int fq) const {
;     ...
;         for (int ai = 0; ai < 2; ++ai) { u32x2 hw[4][2][2];
; #pragma unroll
;             for (int m = 0; m < 4; ++m)
; #pragma unroll
;                 for (int bj = 0; bj < 2; ++bj)
; #pragma unroll
;                     for (int n = 0; n < 2; ++n) hw[m][bj][n] = *(const u32x2*)(H1B + (size_t)(row0 + ai * HALF + m * 16) * 4096 + col0 + bj * HALF + n * 16);
; #pragma unroll
;             for (int m = 0; m < 4; ++m) { const int row = row0 + ai * HALF + m * 16;
;                 float* dst = (row >= 272 && row < G_MV) ? yp + (size_t)(row - 272) * 4096 : nullptr;
;                 if (dst) {
; #pragma unroll
;                     for (int bj = 0; bj < 2; ++bj)
; #pragma unroll
;                         for (int n = 0; n < 2; ++n) { const int c = col0 + bj * HALF + n * 16; const u32x2 w = hw[m][bj][n]; f32x4 h;
;                             h[0] = __builtin_bit_cast(float, w.x << 16); h[1] = __builtin_bit_cast(float, w.x & 0xffff0000u); h[2] = __builtin_bit_cast(float, w.y << 16); h[3] = __builtin_bit_cast(float, w.y & 0xffff0000u);
;                             *(f32x4*)(dst + c) = h + acc[ai][bj][m][n]; } } } }
.LBB0_3532:
	s_or_b64 exec, exec, s[38:39]
	s_nop 0
	v_add_u32_e32 v82, 0xffffff20, v146
	v_cmp_gt_u32_e32 vcc, s55, v82
	s_and_b64 s[4:5], vcc, s[22:23]
	s_and_saveexec_b64 s[38:39], s[4:5]
	s_cbranch_execz .LBB0_3534
	v_lshlrev_b32_e32 v134, 14, v82
	v_lshl_add_u64 v[82:83], s[8:9], 0, v[134:135]
	s_waitcnt vmcnt(0)
	v_lshlrev_b32_e32 v84, 16, v158
	v_and_b32_e32 v85, 0xffff0000, v158
	v_lshlrev_b32_e32 v86, 16, v159
	v_and_b32_e32 v87, 0xffff0000, v159
	v_pk_add_f32 v[80:81], v[80:81], v[86:87]
	v_pk_add_f32 v[78:79], v[78:79], v[84:85]
	v_lshl_add_u64 v[82:83], v[144:145], 2, v[82:83]
	global_store_dwordx4 v[82:83], v[78:81], off nt
	s_nop 1
	v_lshlrev_b32_e32 v78, 16, v156
	v_and_b32_e32 v79, 0xffff0000, v156
	v_lshlrev_b32_e32 v80, 16, v157
	v_and_b32_e32 v81, 0xffff0000, v157
	v_pk_add_f32 v[76:77], v[76:77], v[80:81]
	v_pk_add_f32 v[74:75], v[74:75], v[78:79]
	global_store_dwordx4 v[82:83], v[74:77], off offset:64 nt
	s_nop 1
	v_lshlrev_b32_e32 v74, 16, v154
	v_and_b32_e32 v75, 0xffff0000, v154
	v_lshlrev_b32_e32 v76, 16, v155
	v_and_b32_e32 v77, 0xffff0000, v155
	v_pk_add_f32 v[72:73], v[72:73], v[76:77]
	v_pk_add_f32 v[70:71], v[70:71], v[74:75]
	global_store_dwordx4 v[82:83], v[70:73], off offset:512 nt
	s_nop 1
	v_lshlrev_b32_e32 v70, 16, v152
	v_and_b32_e32 v71, 0xffff0000, v152
	v_lshlrev_b32_e32 v72, 16, v153
	v_and_b32_e32 v73, 0xffff0000, v153
	v_pk_add_f32 v[68:69], v[68:69], v[72:73]
	v_pk_add_f32 v[66:67], v[66:67], v[70:71]
	global_store_dwordx4 v[82:83], v[66:69], off offset:576 nt
.LBB0_3534:
	s_or_b64 exec, exec, s[38:39]
	v_ashrrev_i32_e32 v147, 31, v146
	v_lshlrev_b64 v[66:67], 13, v[146:147]
	v_lshl_add_u64 v[66:67], v[148:149], 0, v[66:67]
	v_add_co_u32_e32 v70, vcc, 0x120000, v66
	v_lshl_add_u64 v[68:69], v[66:67], 0, s[24:25]
	s_nop 0
	v_addc_co_u32_e32 v71, vcc, 0, v67, vcc
	global_load_dwordx2 v[88:89], v[70:71], off
	global_load_dwordx2 v[86:87], v[68:69], off offset:32
	global_load_dwordx2 v[84:85], v[68:69], off offset:256
	global_load_dwordx2 v[82:83], v[68:69], off offset:288
	v_add_co_u32_e32 v70, vcc, 0x140000, v66
	v_lshl_add_u64 v[68:69], v[66:67], 0, s[26:27]
	s_nop 0
	v_addc_co_u32_e32 v71, vcc, 0, v67, vcc
	v_lshl_add_u64 v[90:91], v[66:67], 0, s[28:29]
	v_add_co_u32_e32 v66, vcc, 0x160000, v66
	global_load_dwordx2 v[80:81], v[70:71], off
	global_load_dwordx2 v[78:79], v[68:69], off offset:32
	global_load_dwordx2 v[76:77], v[68:69], off offset:256
	global_load_dwordx2 v[74:75], v[68:69], off offset:288
	v_addc_co_u32_e32 v67, vcc, 0, v67, vcc
	global_load_dwordx2 v[72:73], v[66:67], off
	global_load_dwordx2 v[70:71], v[90:91], off offset:32
	global_load_dwordx2 v[68:69], v[90:91], off offset:256
	s_nop 0
	global_load_dwordx2 v[66:67], v[90:91], off offset:288
	v_add_u32_e32 v90, 0xffffff70, v146
	v_cmp_gt_u32_e32 vcc, s55, v90
	s_and_b64 s[4:5], vcc, s[22:23]
	s_and_saveexec_b64 s[38:39], s[4:5]
	s_cbranch_execz .LBB0_3536
	v_mov_b32_e32 v151, v135
	v_lshl_add_u64 v[92:93], v[148:149], 0, v[150:151]
	v_add_co_u32_e32 v92, vcc, 0x100000, v92
	v_lshlrev_b32_e32 v134, 14, v90
	s_nop 0
	v_addc_co_u32_e32 v93, vcc, 0, v93, vcc
	global_load_dwordx2 v[94:95], v[92:93], off
	global_load_dwordx2 v[96:97], v[92:93], off offset:32
	global_load_dwordx2 v[98:99], v[92:93], off offset:256
	s_nop 0
	global_load_dwordx2 v[92:93], v[92:93], off offset:288
	v_lshl_add_u64 v[90:91], s[8:9], 0, v[134:135]
	v_lshl_add_u64 v[90:91], v[144:145], 2, v[90:91]
	s_waitcnt vmcnt(0)
	v_lshlrev_b32_e32 v100, 16, v94
	v_and_b32_e32 v101, 0xffff0000, v94
	v_lshlrev_b32_e32 v94, 16, v95
	v_and_b32_e32 v95, 0xffff0000, v95
	v_lshlrev_b32_e32 v102, 16, v96
	v_and_b32_e32 v103, 0xffff0000, v96
	v_lshlrev_b32_e32 v96, 16, v97
	v_and_b32_e32 v97, 0xffff0000, v97
	v_lshlrev_b32_e32 v104, 16, v98
	v_and_b32_e32 v105, 0xffff0000, v98
	v_lshlrev_b32_e32 v98, 16, v99
	v_and_b32_e32 v99, 0xffff0000, v99
	v_lshlrev_b32_e32 v106, 16, v92
	v_and_b32_e32 v107, 0xffff0000, v92
	v_lshlrev_b32_e32 v92, 16, v93
	v_and_b32_e32 v93, 0xffff0000, v93
	v_pk_add_f32 v[64:65], v[64:65], v[94:95]
	v_pk_add_f32 v[62:63], v[62:63], v[100:101]
	v_pk_add_f32 v[60:61], v[60:61], v[96:97]
	v_pk_add_f32 v[58:59], v[58:59], v[102:103]
	v_pk_add_f32 v[56:57], v[56:57], v[98:99]
	v_pk_add_f32 v[54:55], v[54:55], v[104:105]
	v_pk_add_f32 v[52:53], v[52:53], v[92:93]
	v_pk_add_f32 v[50:51], v[50:51], v[106:107]
	global_store_dwordx4 v[90:91], v[62:65], off nt
	global_store_dwordx4 v[90:91], v[58:61], off offset:64 nt
	global_store_dwordx4 v[90:91], v[54:57], off offset:512 nt
	global_store_dwordx4 v[90:91], v[50:53], off offset:576 nt
;     __device__ __forceinline__ void operator()(const f32x4 (&acc)[2][2][4][2], const Unit& u, int wr, int wc, int fr, int fq) const {
;     ...
;             for (int m = 0; m < 4; ++m) { const int row = row0 + ai * HALF + m * 16;
;                 float* dst = (row >= 272 && row < G_MV) ? yp + (size_t)(row - 272) * 4096 : nullptr;
;                 if (dst) {
; #pragma unroll
;                     for (int bj = 0; bj < 2; ++bj)
; #pragma unroll
;                         for (int n = 0; n < 2; ++n) { const int c = col0 + bj * HALF + n * 16; const u32x2 w = hw[m][bj][n]; f32x4 h;
;                             h[0] = __builtin_bit_cast(float, w.x << 16); h[1] = __builtin_bit_cast(float, w.x & 0xffff0000u); h[2] = __builtin_bit_cast(float, w.y << 16); h[3] = __builtin_bit_cast(float, w.y & 0xffff0000u);
;                             *(f32x4*)(dst + c) = h + acc[ai][bj][m][n]; } } } }
.LBB0_3536:
	s_or_b64 exec, exec, s[38:39]
	s_nop 0
	v_add_u32_e32 v50, 0xffffff80, v146
	v_cmp_gt_u32_e32 vcc, s55, v50
	s_and_b64 s[4:5], vcc, s[22:23]
	s_and_saveexec_b64 s[38:39], s[4:5]
	s_cbranch_execz .LBB0_3538
	v_lshlrev_b32_e32 v134, 14, v50
	v_lshl_add_u64 v[50:51], s[8:9], 0, v[134:135]
	s_waitcnt vmcnt(0)
	v_lshlrev_b32_e32 v52, 16, v88
	v_and_b32_e32 v53, 0xffff0000, v88
	v_lshlrev_b32_e32 v54, 16, v89
	v_and_b32_e32 v55, 0xffff0000, v89
	v_pk_add_f32 v[48:49], v[48:49], v[54:55]
	v_pk_add_f32 v[46:47], v[46:47], v[52:53]
	v_lshl_add_u64 v[50:51], v[144:145], 2, v[50:51]
	global_store_dwordx4 v[50:51], v[46:49], off nt
	s_nop 1
	v_lshlrev_b32_e32 v46, 16, v86
	v_and_b32_e32 v47, 0xffff0000, v86
	v_lshlrev_b32_e32 v48, 16, v87
	v_and_b32_e32 v49, 0xffff0000, v87
	v_pk_add_f32 v[44:45], v[44:45], v[48:49]
	v_pk_add_f32 v[42:43], v[42:43], v[46:47]
	global_store_dwordx4 v[50:51], v[42:45], off offset:64 nt
	s_nop 1
	v_lshlrev_b32_e32 v42, 16, v84
	v_and_b32_e32 v43, 0xffff0000, v84
	v_lshlrev_b32_e32 v44, 16, v85
	v_and_b32_e32 v45, 0xffff0000, v85
	v_pk_add_f32 v[40:41], v[40:41], v[44:45]
	v_pk_add_f32 v[38:39], v[38:39], v[42:43]
	global_store_dwordx4 v[50:51], v[38:41], off offset:512 nt
	s_nop 1
	v_lshlrev_b32_e32 v38, 16, v82
	v_and_b32_e32 v39, 0xffff0000, v82
	v_lshlrev_b32_e32 v40, 16, v83
	v_and_b32_e32 v41, 0xffff0000, v83
	v_pk_add_f32 v[36:37], v[36:37], v[40:41]
	v_pk_add_f32 v[34:35], v[34:35], v[38:39]
	global_store_dwordx4 v[50:51], v[34:37], off offset:576 nt
.LBB0_3538:
	s_or_b64 exec, exec, s[38:39]
	s_nop 0
	v_add_u32_e32 v34, 0xffffff90, v146
	v_cmp_gt_u32_e32 vcc, s55, v34
	s_and_b64 s[4:5], vcc, s[22:23]
	s_and_saveexec_b64 s[38:39], s[4:5]
	s_cbranch_execz .LBB0_3540
	v_lshlrev_b32_e32 v134, 14, v34
	v_lshl_add_u64 v[34:35], s[8:9], 0, v[134:135]
	s_waitcnt vmcnt(0)
	v_lshlrev_b32_e32 v36, 16, v80
	v_and_b32_e32 v37, 0xffff0000, v80
	v_lshlrev_b32_e32 v38, 16, v81
	v_and_b32_e32 v39, 0xffff0000, v81
	v_pk_add_f32 v[32:33], v[32:33], v[38:39]
	v_pk_add_f32 v[30:31], v[30:31], v[36:37]
	v_lshl_add_u64 v[34:35], v[144:145], 2, v[34:35]
	global_store_dwordx4 v[34:35], v[30:33], off nt
	s_nop 1
	v_lshlrev_b32_e32 v30, 16, v78
	v_and_b32_e32 v31, 0xffff0000, v78
	v_lshlrev_b32_e32 v32, 16, v79
	v_and_b32_e32 v33, 0xffff0000, v79
	v_pk_add_f32 v[28:29], v[28:29], v[32:33]
	v_pk_add_f32 v[26:27], v[26:27], v[30:31]
	global_store_dwordx4 v[34:35], v[26:29], off offset:64 nt
	s_nop 1
	v_lshlrev_b32_e32 v26, 16, v76
	v_and_b32_e32 v27, 0xffff0000, v76
	v_lshlrev_b32_e32 v28, 16, v77
	v_and_b32_e32 v29, 0xffff0000, v77
	v_pk_add_f32 v[24:25], v[24:25], v[28:29]
	v_pk_add_f32 v[22:23], v[22:23], v[26:27]
	global_store_dwordx4 v[34:35], v[22:25], off offset:512 nt
	s_nop 1
	v_lshlrev_b32_e32 v22, 16, v74
	v_and_b32_e32 v23, 0xffff0000, v74
	v_lshlrev_b32_e32 v24, 16, v75
	v_and_b32_e32 v25, 0xffff0000, v75
	v_pk_add_f32 v[20:21], v[20:21], v[24:25]
	v_pk_add_f32 v[18:19], v[18:19], v[22:23]
	global_store_dwordx4 v[34:35], v[18:21], off offset:576 nt
.LBB0_3540:
	s_or_b64 exec, exec, s[38:39]
	s_nop 0
	v_add_u32_e32 v18, 0xffffffa0, v146
	v_cmp_gt_u32_e32 vcc, s55, v18
	s_and_b64 s[4:5], vcc, s[22:23]
	s_and_saveexec_b64 s[38:39], s[4:5]
	s_cbranch_execz .LBB0_3542
	v_lshlrev_b32_e32 v134, 14, v18
	v_lshl_add_u64 v[18:19], s[8:9], 0, v[134:135]
	s_waitcnt vmcnt(0)
	v_lshlrev_b32_e32 v20, 16, v72
	v_and_b32_e32 v21, 0xffff0000, v72
	v_lshlrev_b32_e32 v22, 16, v73
	v_and_b32_e32 v23, 0xffff0000, v73
	v_pk_add_f32 v[16:17], v[16:17], v[22:23]
	v_pk_add_f32 v[14:15], v[14:15], v[20:21]
	v_lshl_add_u64 v[18:19], v[144:145], 2, v[18:19]
	global_store_dwordx4 v[18:19], v[14:17], off nt
	s_nop 1
	v_lshlrev_b32_e32 v14, 16, v70
	v_and_b32_e32 v15, 0xffff0000, v70
	v_lshlrev_b32_e32 v16, 16, v71
	v_and_b32_e32 v17, 0xffff0000, v71
	v_pk_add_f32 v[12:13], v[12:13], v[16:17]
	v_pk_add_f32 v[10:11], v[10:11], v[14:15]
	global_store_dwordx4 v[18:19], v[10:13], off offset:64 nt
	s_nop 1
	v_lshlrev_b32_e32 v10, 16, v68
	v_and_b32_e32 v11, 0xffff0000, v68
	v_lshlrev_b32_e32 v12, 16, v69
	v_and_b32_e32 v13, 0xffff0000, v69
	v_pk_add_f32 v[8:9], v[8:9], v[12:13]
	v_pk_add_f32 v[6:7], v[6:7], v[10:11]
	global_store_dwordx4 v[18:19], v[6:9], off offset:512 nt
	s_nop 1
	v_lshlrev_b32_e32 v6, 16, v66
	v_and_b32_e32 v7, 0xffff0000, v66
	v_lshlrev_b32_e32 v8, 16, v67
	v_and_b32_e32 v9, 0xffff0000, v67
	v_pk_add_f32 v[4:5], v[4:5], v[8:9]
	v_pk_add_f32 v[2:3], v[2:3], v[6:7]
	global_store_dwordx4 v[18:19], v[2:5], off offset:576 nt
